# attnA-pingpong-v4: spread LDS-DMA issue, per-phase setprio (softmax phase high)
# speedup vs baseline: 1.0679x; 1.0129x over previous
; #define SBAR() __builtin_amdgcn_sched_barrier(0)
; template <int MODE>
; __device__ __forceinline__ void attn_unit(const UnitArgs& A, char* lds, const int wave_) {
;     ...
;     float l_reg = 0; f32x16 o[4] = {}; bf16x8 qr[4];
;     { const bf16_t* Qw = A.Qb + (long)(qb * QBLK + r32) * NZ + half * 64 + hi * 8;
; #pragma unroll
;       for (int d0 = 0; d0 < 4; ++d0) qr[d0] = *reinterpret_cast<const bf16x8*>(Qw + d0 * 16); }
;     const int sr = tid >> 4, sc = (tid & 15) * 8, vst0 = v_st(sr, sc);
;     const int vbase = (int)(uintptr_t)V_lds + v_rd_base(lane) + (MODE == 0 ? 0 : half * 1024);
;     const int ldk = A.ldk; const unsigned ldoff = (unsigned)(sr * ldk + sc) * 2u;
;     struct { bf16x8 vs0, vs1; } sr_[1];
;     const unsigned kdoff = (unsigned)(sr * ldk + (((tid & 15) ^ (sr & 7)) * 8)) * 2u;
;     const unsigned kdst0 = (unsigned)__builtin_amdgcn_readfirstlane((int)((unsigned)(uintptr_t)K_lds + (unsigned)wid * 1024u));
;     ...
;     auto zone_of = [&](int t) -> int { const int k0 = 64 * t, qw0 = A.q0 + 32 * qb; return (k0 + 63 - qw0 <= -128) ? 0 : ((k0 - qw0 - 31 >= 128) ? 2 : 1); };
;     ...
;     auto post = [&](f32x16& p0, f32x16& p1, int t) {
;         SBAR();
;         if (MODE == 0) {
;             if (zone_of(t) == 1) { const int k0 = 64 * t, qw0 = A.q0 + 32 * qb;
;                 const float* b = lutA + A.h * LUTA_STRIDE + (k0 - qw0 - r32 + 4 * hi + 320);
; #pragma unroll
;                 for (int r = 0; r < 16; ++r) { const int c = (r & 3) + 8 * (r >> 2); p0[r] += b[c]; p1[r] += b[32 + c]; } }
;         } else if (MODE == 1) {
;             const int kr = A.tile0 + t, rq = A.q0 + (qb >> 1);
;             int rs = rq - 4; rs = rs < 0 ? 0 : rs; rs = rs > A.R - 8 ? A.R - 8 : rs;
;             if (kr < rs || kr >= rs + 8) {
; #pragma unroll
;                 for (int r = 0; r < 16; ++r) { p0[r] = NEG; p1[r] = NEG; }
;             } else {
;                 const int c = 32 * (qb & 1) + r32; int cs = c - 8; cs = cs < 0 ? 0 : cs; cs = cs > 48 ? 48 : cs;
;                 const float* b = lutB + ((2 * A.h + half) * 15 + (kr - rq + 7)) * 128 + 64 + 4 * hi - c;
; #pragma unroll
;                 for (int r = 0; r < 16; ++r) { const int cc = (r & 3) + 8 * (r >> 2), j = 4 * hi + cc;
;                     p0[r] = ((unsigned)(j - cs) < 16u) ? p0[r] + b[cc] : NEG; p1[r] = ((unsigned)(j + 32 - cs) < 16u) ? p1[r] + b[32 + cc] : NEG; } }
;         }
;         SBAR();
;     };
.LBB0_314:
	s_add_i32 s84, s8, s7
	s_mul_i32 s3, s84, 0x1400
	s_mul_hi_u32 s2, s84, 0x1400
	s_add_u32 s17, s37, s3
	s_addc_u32 s18, s38, s2
	s_lshl_b32 s2, s6, 7
	s_ashr_i32 s3, s2, 31
	s_lshl_b64 s[2:3], s[2:3], 1
	s_add_u32 s24, s17, s2
	s_addc_u32 s25, s18, s3
	s_mul_i32 s31, s7, 0x1400
	s_mul_hi_u32 s30, s7, 0x1400
	s_add_u32 s6, s37, s31
	s_addc_u32 s7, s38, s30
	s_add_u32 s6, s6, s2
	s_addc_u32 s7, s7, s3
	s_and_b32 s18, s1, 3
	v_and_b32_e32 v156, 31, v40
	s_lshl_b32 s28, s18, 5
	v_or_b32_e32 v0, s28, v156
	s_ashr_i32 s17, s0, 8
	v_mul_u32_u24_e32 v144, 0x1400, v0
	v_lshl_add_u64 v[0:1], s[24:25], 0, v[144:145]
	s_lshl_b32 s24, s17, 6
	v_bfe_u32 v157, v40, 5, 1
	s_ashr_i32 s25, s24, 31
	v_lshl_add_u64 v[0:1], s[24:25], 1, v[0:1]
	v_lshlrev_b32_e32 v136, 4, v157
	v_mov_b32_e32 v137, v145
	v_lshl_add_u64 v[0:1], v[0:1], 0, v[136:137]
	global_load_dwordx4 v[108:111], v[0:1], off
	global_load_dwordx4 v[104:107], v[0:1], off offset:32
	global_load_dwordx4 v[100:103], v[0:1], off offset:64
	global_load_dwordx4 v[96:99], v[0:1], off offset:96
	s_add_u32 s24, s6, 0x400
	s_addc_u32 s25, s7, 0
	s_add_u32 s26, s6, 0x800
	s_addc_u32 s27, s7, 0
	v_and_b32_e32 v137, 63, v40
	v_lshlrev_b32_e32 v176, 8, v156
	v_and_b32_e32 v178, 7, v156
	v_lshlrev_b32_e32 v178, 4, v178
	s_lshl_b32 s101, s17, 7
	v_or_b32_e32 v179, s101, v136
	v_xor_b32_e32 v179, v179, v178
	v_add_u32_e32 v176, v176, v179
	v_add_u32_e32 v164, 0x8000, v176
	v_xor_b32_e32 v165, 32, v164
	v_xor_b32_e32 v166, 64, v164
	v_xor_b32_e32 v167, 0x60, v164
	v_and_b32_e32 v176, 3, v137
	v_lshlrev_b32_e32 v176, 3, v176
	v_bfe_u32 v178, v137, 2, 2
	v_lshlrev_b32_e32 v178, 6, v178
	v_bfe_u32 v179, v137, 4, 1
	v_lshlrev_b32_e32 v179, 5, v179
	v_bfe_u32 v180, v137, 5, 1
	v_lshlrev_b32_e32 v180, 8, v180
	v_or3_b32 v176, v176, v178, v179
	v_or_b32_e32 v168, v176, v180
	v_lshrrev_b32_e32 v176, 4, v40
	v_and_b32_e32 v178, 15, v40
	v_and_b32_e32 v179, 7, v176
	v_xor_b32_e32 v178, v178, v179
	v_lshlrev_b32_e32 v178, 4, v178
	v_mul_u32_u24_e32 v176, 0x1400, v176
	v_add_u32_e32 v169, v176, v178
	v_add_u32_e32 v170, 0x28000, v169
	v_bfe_u32 v176, v137, 2, 3
	v_and_b32_e32 v178, 3, v176
	v_lshrrev_b32_e32 v176, 2, v176
	v_lshl_or_b32 v178, v176, 3, v178
	s_bfe_u32 s101, s1, 0x10001
	s_lshl_b32 s101, s101, 2
	s_bfe_u32 s6, s1, 0x10002
	s_lshl_b32 s6, s6, 4
	s_or_b32 s101, s101, s6
	v_or_b32_e32 v178, s101, v178
	v_mul_u32_u24_e32 v178, 0x1400, v178
	s_and_b32 s101, s1, 1
	s_lshl_b32 s101, s101, 7
	v_bfe_u32 v176, v137, 5, 1
	v_lshlrev_b32_e32 v176, 6, v176
	v_and_b32_e32 v179, 3, v137
	v_lshlrev_b32_e32 v179, 4, v179
	v_add3_u32 v178, v178, v176, v179
	v_add_u32_e32 v171, s101, v178
	v_add_u32_e32 v172, 0x28000, v171
	s_lshl_b32 s33, s1, 10
	s_add_u32 s31, s33, 0x8000
	s_add_i32 s101, s8, s28
	s_sub_i32 s29, s101, 0xbf
	s_add_i32 s30, s101, 0x9f
	s_sub_i32 s35, 0x140, s101
	s_lshl_b32 s35, s35, 2
	s_add_i32 s35, s35, s19
	v_lshlrev_b32_e32 v176, 2, v157
	v_sub_u32_e32 v176, v176, v156
	v_lshlrev_b32_e32 v174, 2, v176
	v_mov_b32_e32 v176, s13
	v_sub_f32_e32 v178, s21, v176
	v_sub_f32_e32 v179, s20, v176
	s_xor_b32 s99, s13, 0x80000000
	v_readfirstlane_b32 s98, v178
	v_readfirstlane_b32 s100, v179
	s_sub_i32 s20, s22, 1
	s_mov_b32 s34, 0
	s_mov_b32 s23, 0
	s_cmp_le_i32 s23, s29
	s_cselect_b32 s9, s98, s99
	v_mov_b32_e32 v68, s9
	v_mov_b32_e32 v69, s9
	v_mov_b32_e32 v70, s9
	v_mov_b32_e32 v71, s9
	v_mov_b32_e32 v72, s9
	v_mov_b32_e32 v73, s9
	v_mov_b32_e32 v74, s9
	v_mov_b32_e32 v75, s9
	v_mov_b32_e32 v76, s9
	v_mov_b32_e32 v77, s9
	v_mov_b32_e32 v78, s9
	v_mov_b32_e32 v79, s9
	v_mov_b32_e32 v80, s9
	v_mov_b32_e32 v81, s9
	v_mov_b32_e32 v82, s9
	v_mov_b32_e32 v83, s9
	v_mov_b32_e32 v0, 0
	v_mov_b32_e32 v1, 0
	v_mov_b32_e32 v2, 0
	v_mov_b32_e32 v3, 0
	v_mov_b32_e32 v4, 0
	v_mov_b32_e32 v5, 0
	v_mov_b32_e32 v6, 0
	v_mov_b32_e32 v7, 0
	v_mov_b32_e32 v8, 0
	v_mov_b32_e32 v9, 0
	v_mov_b32_e32 v10, 0
	v_mov_b32_e32 v11, 0
	v_mov_b32_e32 v12, 0
	v_mov_b32_e32 v13, 0
	v_mov_b32_e32 v14, 0
	v_mov_b32_e32 v15, 0
	v_mov_b32_e32 v16, 0
	v_mov_b32_e32 v17, 0
	v_mov_b32_e32 v18, 0
	v_mov_b32_e32 v19, 0
	v_mov_b32_e32 v20, 0
	v_mov_b32_e32 v21, 0
	v_mov_b32_e32 v22, 0
	v_mov_b32_e32 v23, 0
	v_mov_b32_e32 v24, 0
	v_mov_b32_e32 v25, 0
	v_mov_b32_e32 v26, 0
	v_mov_b32_e32 v27, 0
	v_mov_b32_e32 v28, 0
	v_mov_b32_e32 v29, 0
	v_mov_b32_e32 v30, 0
	v_mov_b32_e32 v31, 0
	v_mov_b32_e32 v32, 0
	v_mov_b32_e32 v33, 0
	v_mov_b32_e32 v34, 0
	v_mov_b32_e32 v35, 0
	v_mov_b32_e32 v36, 0
	v_mov_b32_e32 v37, 0
	v_mov_b32_e32 v38, 0
	v_mov_b32_e32 v39, 0
	v_mov_b32_e32 v40, 0
	v_mov_b32_e32 v41, 0
	v_mov_b32_e32 v42, 0
	v_mov_b32_e32 v43, 0
	v_mov_b32_e32 v44, 0
	v_mov_b32_e32 v45, 0
	v_mov_b32_e32 v46, 0
	v_mov_b32_e32 v47, 0
	v_mov_b32_e32 v48, 0
	v_mov_b32_e32 v49, 0
	v_mov_b32_e32 v50, 0
	v_mov_b32_e32 v51, 0
	v_mov_b32_e32 v52, 0
	v_mov_b32_e32 v53, 0
	v_mov_b32_e32 v54, 0
	v_mov_b32_e32 v55, 0
	v_mov_b32_e32 v56, 0
	v_mov_b32_e32 v57, 0
	v_mov_b32_e32 v58, 0
	v_mov_b32_e32 v59, 0
	v_mov_b32_e32 v60, 0
	v_mov_b32_e32 v61, 0
	v_mov_b32_e32 v62, 0
	v_mov_b32_e32 v63, 0
	v_mov_b32_e32 v64, 0
	v_mov_b32_e32 v65, 0
	v_mov_b32_e32 v66, 0
	v_mov_b32_e32 v67, 0
	s_mov_b32 m0, s31
	s_add_u32 s101, s31, 0x2000
	global_load_lds_dwordx4 v169, s[24:25]
	s_mov_b32 m0, s101
	s_xor_b32 s31, s31, 0x4000
	global_load_lds_dwordx4 v170, s[24:25]
	s_add_u32 s24, s24, 0x50000
	s_addc_u32 s25, s25, 0
	s_mov_b32 m0, s31
	s_add_u32 s101, s31, 0x2000
	global_load_lds_dwordx4 v169, s[24:25]
	s_mov_b32 m0, s101
	s_xor_b32 s31, s31, 0x4000
	global_load_lds_dwordx4 v170, s[24:25]
	s_add_u32 s24, s24, 0x50000
	s_addc_u32 s25, s25, 0
	s_mov_b32 m0, s33
	s_add_u32 s101, s33, 0x2000
	global_load_lds_dwordx4 v171, s[26:27]
	s_mov_b32 m0, s101
	s_xor_b32 s33, s33, 0x4000
	global_load_lds_dwordx4 v172, s[26:27]
	s_add_u32 s26, s26, 0x50000
	s_addc_u32 s27, s27, 0
	s_waitcnt vmcnt(0)
	s_barrier
; #define SBAR() __builtin_amdgcn_sched_barrier(0)
; #define KFRAG(d0, row) (*reinterpret_cast<const bf16x8*>(Ks + KSWZ((row), (half * 64 + (d0) * 16 + hi * 8) * 2)))
; __device__ __forceinline__ void qkt(f32x16& p0, f32x16& p1, const char* Ks, const bf16x8* qr, float c0, int r32, int hi, int half) {
;     ...
;     bf16x8 a0 = KFRAG(0, r32), a1 = KFRAG(0, 32 + r32), b0 = KFRAG(1, r32), b1 = KFRAG(1, 32 + r32);
;     SBAR();
; #pragma unroll
;     for (int r = 0; r < 16; ++r) { p0[r] = c0; p1[r] = c0; }
;     SBAR();
;     p0 = __builtin_amdgcn_mfma_f32_32x32x16_bf16(a0, qr[0], p0, 0, 0, 0); p1 = __builtin_amdgcn_mfma_f32_32x32x16_bf16(a1, qr[0], p1, 0, 0, 0);
;     a0 = KFRAG(2, r32); a1 = KFRAG(2, 32 + r32);
;     SBAR();
;     p0 = __builtin_amdgcn_mfma_f32_32x32x16_bf16(b0, qr[1], p0, 0, 0, 0); p1 = __builtin_amdgcn_mfma_f32_32x32x16_bf16(b1, qr[1], p1, 0, 0, 0);
;     b0 = KFRAG(3, r32); b1 = KFRAG(3, 32 + r32);
;     SBAR();
;     p0 = __builtin_amdgcn_mfma_f32_32x32x16_bf16(a0, qr[2], p0, 0, 0, 0); p1 = __builtin_amdgcn_mfma_f32_32x32x16_bf16(a1, qr[2], p1, 0, 0, 0);
;     p0 = __builtin_amdgcn_mfma_f32_32x32x16_bf16(b0, qr[3], p0, 0, 0, 0); p1 = __builtin_amdgcn_mfma_f32_32x32x16_bf16(b1, qr[3], p1, 0, 0, 0);
; template <int MODE>
; __device__ __forceinline__ void attn_unit(const UnitArgs& A, char* lds, const int wave_) {
;     ...
;     auto post = [&](f32x16& p0, f32x16& p1, int t) {
;         SBAR();
;         if (MODE == 0) {
;             if (zone_of(t) == 1) { const int k0 = 64 * t, qw0 = A.q0 + 32 * qb;
;                 const float* b = lutA + A.h * LUTA_STRIDE + (k0 - qw0 - r32 + 4 * hi + 320);
; #pragma unroll
;                 for (int r = 0; r < 16; ++r) { const int c = (r & 3) + 8 * (r >> 2); p0[r] += b[c]; p1[r] += b[32 + c]; } }
	s_cmp_lg_u32 s17, 0
	s_cbranch_scc1 .Lat_g1
	s_setprio 0
	ds_read_b128 v[224:227], v164
	ds_read_b128 v[228:231], v164 offset:8192
	ds_read_b128 v[232:235], v165
	ds_read_b128 v[236:239], v165 offset:8192
	ds_read_b128 v[240:243], v166
	ds_read_b128 v[244:247], v166 offset:8192
	ds_read_b128 v[248:251], v167
	ds_read_b128 v[188:191], v167 offset:8192
	v_xor_b32_e32 v164, 0x4000, v164
	v_xor_b32_e32 v165, 0x4000, v165
	v_xor_b32_e32 v166, 0x4000, v166
	v_xor_b32_e32 v167, 0x4000, v167
	s_waitcnt lgkmcnt(7)
	v_mfma_f32_32x32x16_bf16 v[112:127], v[224:227], v[108:111], v[68:83]
	s_waitcnt lgkmcnt(6)
	v_mfma_f32_32x32x16_bf16 v[192:207], v[228:231], v[108:111], v[68:83]
	s_waitcnt lgkmcnt(5)
	v_mfma_f32_32x32x16_bf16 v[112:127], v[232:235], v[104:107], v[112:127]
	s_waitcnt lgkmcnt(4)
	v_mfma_f32_32x32x16_bf16 v[192:207], v[236:239], v[104:107], v[192:207]
	s_waitcnt lgkmcnt(3)
	v_mfma_f32_32x32x16_bf16 v[112:127], v[240:243], v[100:103], v[112:127]
	s_waitcnt lgkmcnt(2)
	v_mfma_f32_32x32x16_bf16 v[192:207], v[244:247], v[100:103], v[192:207]
	s_waitcnt lgkmcnt(1)
	v_mfma_f32_32x32x16_bf16 v[112:127], v[248:251], v[96:99], v[112:127]
	s_waitcnt lgkmcnt(0)
	v_mfma_f32_32x32x16_bf16 v[192:207], v[188:191], v[96:99], v[192:207]
	s_nop 7
	s_nop 3
	s_barrier
.Lat_g0_loop:
	s_setprio 1
	s_cmp_gt_i32 s23, s29
	s_cselect_b32 s101, 1, 0
	s_cmp_lt_i32 s23, s30
	s_cselect_b32 s6, 1, 0
	s_and_b32 s101, s101, s6
	s_cbranch_scc0 .Lat_far_g0l
	v_add_u32_e32 v181, s35, v174
	ds_read2_b32 v[224:225], v181 offset0:0 offset1:1
	ds_read2_b32 v[226:227], v181 offset0:2 offset1:3
	ds_read2_b32 v[228:229], v181 offset0:8 offset1:9
	ds_read2_b32 v[230:231], v181 offset0:10 offset1:11
	ds_read2_b32 v[232:233], v181 offset0:16 offset1:17
	ds_read2_b32 v[234:235], v181 offset0:18 offset1:19
	ds_read2_b32 v[236:237], v181 offset0:24 offset1:25
	ds_read2_b32 v[238:239], v181 offset0:26 offset1:27
	s_waitcnt lgkmcnt(4)
	ds_read2_b32 v[240:241], v181 offset0:32 offset1:33
	ds_read2_b32 v[242:243], v181 offset0:34 offset1:35
	ds_read2_b32 v[244:245], v181 offset0:40 offset1:41
	ds_read2_b32 v[246:247], v181 offset0:42 offset1:43
	ds_read2_b32 v[248:249], v181 offset0:48 offset1:49
	ds_read2_b32 v[250:251], v181 offset0:50 offset1:51
	ds_read2_b32 v[188:189], v181 offset0:56 offset1:57
	ds_read2_b32 v[190:191], v181 offset0:58 offset1:59
	s_waitcnt lgkmcnt(8)
	v_add_f32_e32 v112, v112, v224
	v_add_f32_e32 v113, v113, v225
	v_add_f32_e32 v114, v114, v226
	v_add_f32_e32 v115, v115, v227
	v_add_f32_e32 v116, v116, v228
	v_add_f32_e32 v117, v117, v229
	v_add_f32_e32 v118, v118, v230
	v_add_f32_e32 v119, v119, v231
	v_add_f32_e32 v120, v120, v232
	v_add_f32_e32 v121, v121, v233
	v_add_f32_e32 v122, v122, v234
	v_add_f32_e32 v123, v123, v235
	v_add_f32_e32 v124, v124, v236
	v_add_f32_e32 v125, v125, v237
	v_add_f32_e32 v126, v126, v238
	v_add_f32_e32 v127, v127, v239
	s_waitcnt lgkmcnt(0)
	v_add_f32_e32 v192, v192, v240
	v_add_f32_e32 v193, v193, v241
	v_add_f32_e32 v194, v194, v242
	v_add_f32_e32 v195, v195, v243
	v_add_f32_e32 v196, v196, v244
	v_add_f32_e32 v197, v197, v245
	v_add_f32_e32 v198, v198, v246
	v_add_f32_e32 v199, v199, v247
	v_add_f32_e32 v200, v200, v248
	v_add_f32_e32 v201, v201, v249
	v_add_f32_e32 v202, v202, v250
	v_add_f32_e32 v203, v203, v251
	v_add_f32_e32 v204, v204, v188
	v_add_f32_e32 v205, v205, v189
	v_add_f32_e32 v206, v206, v190
	v_add_f32_e32 v207, v207, v191

; #define SBAR() __builtin_amdgcn_sched_barrier(0)
; __device__ __forceinline__ void qkt(f32x16& p0, f32x16& p1, const char* Ks, const bf16x8* qr, float c0, int r32, int hi, int half) {
;     ...
;     bf16x8 a0 = KFRAG(0, r32), a1 = KFRAG(0, 32 + r32), b0 = KFRAG(1, r32), b1 = KFRAG(1, 32 + r32);
;     SBAR();
; #pragma unroll
;     for (int r = 0; r < 16; ++r) { p0[r] = c0; p1[r] = c0; }
;     SBAR();
;     p0 = __builtin_amdgcn_mfma_f32_32x32x16_bf16(a0, qr[0], p0, 0, 0, 0); p1 = __builtin_amdgcn_mfma_f32_32x32x16_bf16(a1, qr[0], p1, 0, 0, 0);
;     a0 = KFRAG(2, r32); a1 = KFRAG(2, 32 + r32);
;     SBAR();
;     p0 = __builtin_amdgcn_mfma_f32_32x32x16_bf16(b0, qr[1], p0, 0, 0, 0); p1 = __builtin_amdgcn_mfma_f32_32x32x16_bf16(b1, qr[1], p1, 0, 0, 0);
;     b0 = KFRAG(3, r32); b1 = KFRAG(3, 32 + r32);
;     SBAR();
;     p0 = __builtin_amdgcn_mfma_f32_32x32x16_bf16(a0, qr[2], p0, 0, 0, 0); p1 = __builtin_amdgcn_mfma_f32_32x32x16_bf16(a1, qr[2], p1, 0, 0, 0);
;     p0 = __builtin_amdgcn_mfma_f32_32x32x16_bf16(b0, qr[3], p0, 0, 0, 0); p1 = __builtin_amdgcn_mfma_f32_32x32x16_bf16(b1, qr[3], p1, 0, 0, 0);
;     ...
; }
; __device__ __forceinline__ int v_st(int k, int c) { const int kk = (k & ~0xC) | ((k & 4) << 1) | ((k & 8) >> 1); return ((kk >> 3) * 4 + (c >> 5)) * 512 + ((kk & 7) * 32 + (c & 31)) * 2; }
; __device__ __forceinline__ int v_rd_base(int lane) { return ((lane & 3) << 3) | (((lane >> 2) & 3) << 6) | (((lane >> 4) & 1) << 5) | (((lane >> 5) & 1) << 8); }
; template <int OFF> __device__ __forceinline__ s16x4 tr_read(int vb) { s16x4 r; asm volatile("ds_read_b64_tr_b16 %0, %1 offset:%2" : "=&v"(r) : "v"(vb), "i"(OFF) : "memory"); return r; }
; template <int NB> __device__ __forceinline__ void pv_blocks(f32x16* o, int vb, bf16x8 pa0, bf16x8 pa1, bf16x8 pa2, bf16x8 pa3, f32x16& pe0, f32x16& pe1) {
;     s16x4 x[8], y[8];
;     ...
;     PVLOAD(0, x); PVWAIT();
;     if (NB == 4) {
;         PVLOAD(1, y); SBAR(); PVMMA(o[0], x); PVEXP(pe0, 0, 8); SBAR(); PVWAIT();
;         PVLOAD(2, x); SBAR(); PVMMA(o[1], y); PVEXP(pe0, 8, 8); SBAR(); PVWAIT();
;         PVLOAD(3, y); SBAR(); PVMMA(o[2], x); PVEXP(pe1, 0, 8); SBAR(); PVWAIT();
;         PVMMA(o[3], y); PVEXP(pe1, 8, 8);
;     } else {
;         PVLOAD(1, y); SBAR(); PVMMA(o[0], x); PVEXP(pe0, 0, 16); SBAR(); PVWAIT();
;         PVMMA(o[1], y); PVEXP(pe1, 0, 16);
;     }
;     ...
; }
.Lat_c0same_g0l:
	s_waitcnt vmcnt(0)
	s_barrier
	s_setprio 0
	ds_read_b128 v[224:227], v164
	ds_read_b128 v[228:231], v164 offset:8192
	ds_read_b128 v[232:235], v165
	ds_read_b128 v[236:239], v165 offset:8192
	ds_read_b128 v[240:243], v166
	ds_read_b128 v[244:247], v166 offset:8192
	ds_read_b128 v[248:251], v167
	ds_read_b128 v[188:191], v167 offset:8192
	v_xor_b32_e32 v164, 0x4000, v164
	v_xor_b32_e32 v165, 0x4000, v165
	v_xor_b32_e32 v166, 0x4000, v166
	v_xor_b32_e32 v167, 0x4000, v167
	s_waitcnt lgkmcnt(7)
	v_mfma_f32_32x32x16_bf16 v[112:127], v[224:227], v[108:111], v[68:83]
	s_waitcnt lgkmcnt(6)
	v_mfma_f32_32x32x16_bf16 v[192:207], v[228:231], v[108:111], v[68:83]
	ds_read_b64_tr_b16 v[84:85], v168 offset:0
	ds_read_b64_tr_b16 v[86:87], v168 offset:2048
	s_waitcnt lgkmcnt(7)
	v_mfma_f32_32x32x16_bf16 v[112:127], v[232:235], v[104:107], v[112:127]
	ds_read_b64_tr_b16 v[88:89], v168 offset:4096
	ds_read_b64_tr_b16 v[90:91], v168 offset:6144
	s_waitcnt lgkmcnt(8)
	v_mfma_f32_32x32x16_bf16 v[192:207], v[236:239], v[104:107], v[192:207]
	ds_read_b64_tr_b16 v[92:93], v168 offset:8192
	ds_read_b64_tr_b16 v[94:95], v168 offset:10240
	s_waitcnt lgkmcnt(9)
	v_mfma_f32_32x32x16_bf16 v[112:127], v[240:243], v[100:103], v[112:127]
	ds_read_b64_tr_b16 v[128:129], v168 offset:12288
	ds_read_b64_tr_b16 v[130:131], v168 offset:14336
	s_waitcnt lgkmcnt(10)
	v_mfma_f32_32x32x16_bf16 v[192:207], v[244:247], v[100:103], v[192:207]
	ds_read_b64_tr_b16 v[132:133], v168 offset:512
	ds_read_b64_tr_b16 v[134:135], v168 offset:2560
	s_waitcnt lgkmcnt(11)
	v_mfma_f32_32x32x16_bf16 v[112:127], v[248:251], v[96:99], v[112:127]
	ds_read_b64_tr_b16 v[140:141], v168 offset:4608
	ds_read_b64_tr_b16 v[142:143], v168 offset:6656
	s_waitcnt lgkmcnt(12)
	v_mfma_f32_32x32x16_bf16 v[192:207], v[188:191], v[96:99], v[192:207]
	ds_read_b64_tr_b16 v[152:153], v168 offset:8704
	ds_read_b64_tr_b16 v[154:155], v168 offset:10752
	s_waitcnt lgkmcnt(12)
	v_mfma_f32_32x32x16_bf16 v[0:15], v[208:211], v[84:87], v[0:15]
	ds_read_b64_tr_b16 v[160:161], v168 offset:12800
	ds_read_b64_tr_b16 v[162:163], v168 offset:14848
	s_waitcnt lgkmcnt(12)
	v_mfma_f32_32x32x16_bf16 v[0:15], v[212:215], v[88:91], v[0:15]
	ds_read_b64_tr_b16 v[84:85], v168 offset:1024
	ds_read_b64_tr_b16 v[86:87], v168 offset:3072
	s_waitcnt lgkmcnt(12)
	v_mfma_f32_32x32x16_bf16 v[0:15], v[216:219], v[92:95], v[0:15]
	ds_read_b64_tr_b16 v[88:89], v168 offset:5120
	ds_read_b64_tr_b16 v[90:91], v168 offset:7168
	s_waitcnt lgkmcnt(12)
	v_mfma_f32_32x32x16_bf16 v[0:15], v[220:223], v[128:131], v[0:15]
	ds_read_b64_tr_b16 v[92:93], v168 offset:9216
	ds_read_b64_tr_b16 v[94:95], v168 offset:11264
	s_waitcnt lgkmcnt(12)
	v_mfma_f32_32x32x16_bf16 v[16:31], v[208:211], v[132:135], v[16:31]
	ds_read_b64_tr_b16 v[128:129], v168 offset:13312
	ds_read_b64_tr_b16 v[130:131], v168 offset:15360
	s_mov_b32 m0, s31
	s_add_u32 s7, s31, 0x2000
	global_load_lds_dwordx4 v169, s[24:25]
	s_waitcnt lgkmcnt(12)
	v_mfma_f32_32x32x16_bf16 v[16:31], v[212:215], v[140:143], v[16:31]
	ds_read_b64_tr_b16 v[132:133], v168 offset:1536
	ds_read_b64_tr_b16 v[134:135], v168 offset:3584
	s_waitcnt lgkmcnt(12)
	v_mfma_f32_32x32x16_bf16 v[16:31], v[216:219], v[152:155], v[16:31]
	ds_read_b64_tr_b16 v[140:141], v168 offset:5632
	ds_read_b64_tr_b16 v[142:143], v168 offset:7680
	s_waitcnt lgkmcnt(12)
	v_mfma_f32_32x32x16_bf16 v[16:31], v[220:223], v[160:163], v[16:31]
	ds_read_b64_tr_b16 v[152:153], v168 offset:9728
	ds_read_b64_tr_b16 v[154:155], v168 offset:11776
	s_mov_b32 m0, s7
	s_xor_b32 s31, s31, 0x4000
	global_load_lds_dwordx4 v170, s[24:25]
	s_add_u32 s24, s24, 0x50000
	s_addc_u32 s25, s25, 0
	s_waitcnt lgkmcnt(12)
	v_mfma_f32_32x32x16_bf16 v[32:47], v[208:211], v[84:87], v[32:47]
	ds_read_b64_tr_b16 v[160:161], v168 offset:13824
	ds_read_b64_tr_b16 v[162:163], v168 offset:15872
	v_xor_b32_e32 v168, 0x4000, v168
	s_waitcnt lgkmcnt(12)
	v_mfma_f32_32x32x16_bf16 v[32:47], v[212:215], v[88:91], v[32:47]
	s_waitcnt lgkmcnt(10)
	v_mfma_f32_32x32x16_bf16 v[32:47], v[216:219], v[92:95], v[32:47]
	s_mov_b32 m0, s33
	s_add_u32 s7, s33, 0x2000
	global_load_lds_dwordx4 v171, s[26:27]
	s_waitcnt lgkmcnt(8)
	v_mfma_f32_32x32x16_bf16 v[32:47], v[220:223], v[128:131], v[32:47]
	s_waitcnt lgkmcnt(6)
	v_mfma_f32_32x32x16_bf16 v[48:63], v[208:211], v[132:135], v[48:63]
	s_waitcnt lgkmcnt(4)
	v_mfma_f32_32x32x16_bf16 v[48:63], v[212:215], v[140:143], v[48:63]
	s_mov_b32 m0, s7
	s_xor_b32 s33, s33, 0x4000
	global_load_lds_dwordx4 v172, s[26:27]
	s_add_u32 s26, s26, 0x50000
	s_addc_u32 s27, s27, 0
	s_waitcnt lgkmcnt(2)
	v_mfma_f32_32x32x16_bf16 v[48:63], v[216:219], v[152:155], v[48:63]
	s_waitcnt lgkmcnt(0)
	v_mfma_f32_32x32x16_bf16 v[48:63], v[220:223], v[160:163], v[48:63]
	s_add_i32 s34, s34, 1
	s_add_i32 s23, s23, 64
	s_addk_i32 s35, 0x100
	s_barrier
	s_cmp_lt_u32 s34, s20
	s_cbranch_scc1 .Lat_g0_loop
	s_setprio 1
	s_cmp_gt_i32 s23, s29
	s_cselect_b32 s101, 1, 0
	s_cmp_lt_i32 s23, s30
	s_cselect_b32 s6, 1, 0
	s_and_b32 s101, s101, s6
	s_cbranch_scc0 .Lat_far_g0p
	v_add_u32_e32 v181, s35, v174
	ds_read2_b32 v[224:225], v181 offset0:0 offset1:1
	ds_read2_b32 v[226:227], v181 offset0:2 offset1:3
	ds_read2_b32 v[228:229], v181 offset0:8 offset1:9
	ds_read2_b32 v[230:231], v181 offset0:10 offset1:11
	ds_read2_b32 v[232:233], v181 offset0:16 offset1:17
	ds_read2_b32 v[234:235], v181 offset0:18 offset1:19
	ds_read2_b32 v[236:237], v181 offset0:24 offset1:25
	ds_read2_b32 v[238:239], v181 offset0:26 offset1:27
	s_waitcnt lgkmcnt(4)
	ds_read2_b32 v[240:241], v181 offset0:32 offset1:33
	ds_read2_b32 v[242:243], v181 offset0:34 offset1:35
	ds_read2_b32 v[244:245], v181 offset0:40 offset1:41
	ds_read2_b32 v[246:247], v181 offset0:42 offset1:43
	ds_read2_b32 v[248:249], v181 offset0:48 offset1:49
	ds_read2_b32 v[250:251], v181 offset0:50 offset1:51
	ds_read2_b32 v[188:189], v181 offset0:56 offset1:57
	ds_read2_b32 v[190:191], v181 offset0:58 offset1:59
	s_waitcnt lgkmcnt(8)
	v_add_f32_e32 v112, v112, v224
	v_add_f32_e32 v113, v113, v225
	v_add_f32_e32 v114, v114, v226
	v_add_f32_e32 v115, v115, v227
	v_add_f32_e32 v116, v116, v228
	v_add_f32_e32 v117, v117, v229
	v_add_f32_e32 v118, v118, v230
	v_add_f32_e32 v119, v119, v231
	v_add_f32_e32 v120, v120, v232
	v_add_f32_e32 v121, v121, v233
	v_add_f32_e32 v122, v122, v234
	v_add_f32_e32 v123, v123, v235
	v_add_f32_e32 v124, v124, v236
	v_add_f32_e32 v125, v125, v237
	v_add_f32_e32 v126, v126, v238
	v_add_f32_e32 v127, v127, v239
	s_waitcnt lgkmcnt(0)
	v_add_f32_e32 v192, v192, v240
	v_add_f32_e32 v193, v193, v241
	v_add_f32_e32 v194, v194, v242
	v_add_f32_e32 v195, v195, v243
	v_add_f32_e32 v196, v196, v244
	v_add_f32_e32 v197, v197, v245
	v_add_f32_e32 v198, v198, v246
	v_add_f32_e32 v199, v199, v247
	v_add_f32_e32 v200, v200, v248
	v_add_f32_e32 v201, v201, v249
	v_add_f32_e32 v202, v202, v250
	v_add_f32_e32 v203, v203, v251
	v_add_f32_e32 v204, v204, v188
	v_add_f32_e32 v205, v205, v189
	v_add_f32_e32 v206, v206, v190
	v_add_f32_e32 v207, v207, v191
; #define SBAR() __builtin_amdgcn_sched_barrier(0)
; #define PVLOAD(D0, X) do { X[0] = tr_read<v_rd_off(D0, 0, 0)>(vb); X[1] = tr_read<v_rd_off(D0, 0, 1)>(vb); X[2] = tr_read<v_rd_off(D0, 1, 0)>(vb); X[3] = tr_read<v_rd_off(D0, 1, 1)>(vb); \
;     X[4] = tr_read<v_rd_off(D0, 2, 0)>(vb); X[5] = tr_read<v_rd_off(D0, 2, 1)>(vb); X[6] = tr_read<v_rd_off(D0, 3, 0)>(vb); X[7] = tr_read<v_rd_off(D0, 3, 1)>(vb); } while (0)
; #define PVMMA(OD, X) do { OD = __builtin_amdgcn_mfma_f32_32x32x16_bf16(pa0, PVPK(X[0], X[1]), OD, 0, 0, 0); OD = __builtin_amdgcn_mfma_f32_32x32x16_bf16(pa1, PVPK(X[2], X[3]), OD, 0, 0, 0); \
;     OD = __builtin_amdgcn_mfma_f32_32x32x16_bf16(pa2, PVPK(X[4], X[5]), OD, 0, 0, 0); OD = __builtin_amdgcn_mfma_f32_32x32x16_bf16(pa3, PVPK(X[6], X[7]), OD, 0, 0, 0); } while (0)
; #define PVWAIT() do { asm volatile("s_waitcnt lgkmcnt(0)" ::: "memory"); SBAR(); } while (0)
; #define PVEXP(P, B, N) do { _Pragma("unroll") for (int r = (B); r < (B) + (N); ++r) P[r] = __builtin_amdgcn_exp2f(P[r]); } while (0)
; __device__ __forceinline__ void expHalf(f32x16& p0) {
; #pragma unroll
;     for (int r = 0; r < 16; ++r) p0[r] = __builtin_amdgcn_exp2f(p0[r]);
; }
; __device__ __forceinline__ void finishSM(f32x16& p0, f32x16& p1, float& l_reg, bf16x8& pa0, bf16x8& pa1, bf16x8& pa2, bf16x8& pa3) {
;     float ps = 0;
; #pragma unroll
;     for (int r = 0; r < 16; ++r) ps += p0[r];
; #pragma unroll
;     for (int r = 0; r < 16; ++r) ps += p1[r];
;     l_reg += ps;
;     ...
;     PK4(p0, 0, pa0); PK4(p0, 8, pa1); PK4(p1, 0, pa2); PK4(p1, 8, pa3);
;     ...
; }
; template <int NB> __device__ __forceinline__ void pv_blocks(f32x16* o, int vb, bf16x8 pa0, bf16x8 pa1, bf16x8 pa2, bf16x8 pa3, f32x16& pe0, f32x16& pe1) {
;     s16x4 x[8], y[8];
;     ...
;     PVLOAD(0, x); PVWAIT();
;     if (NB == 4) {
;         PVLOAD(1, y); SBAR(); PVMMA(o[0], x); PVEXP(pe0, 0, 8); SBAR(); PVWAIT();
;         PVLOAD(2, x); SBAR(); PVMMA(o[1], y); PVEXP(pe0, 8, 8); SBAR(); PVWAIT();
;         PVLOAD(3, y); SBAR(); PVMMA(o[2], x); PVEXP(pe1, 0, 8); SBAR(); PVWAIT();
;         PVMMA(o[3], y); PVEXP(pe1, 8, 8);
;     } else {
;         PVLOAD(1, y); SBAR(); PVMMA(o[0], x); PVEXP(pe0, 0, 16); SBAR(); PVWAIT();
;         PVMMA(o[1], y); PVEXP(pe1, 0, 16);
;     }
;     ...
; }
.Lat_far_g0p:
	v_exp_f32_e32 v112, v112
	v_exp_f32_e32 v113, v113
	v_exp_f32_e32 v114, v114
	v_exp_f32_e32 v115, v115
	v_exp_f32_e32 v116, v116
	v_exp_f32_e32 v117, v117
	v_exp_f32_e32 v118, v118
	v_exp_f32_e32 v119, v119
	v_exp_f32_e32 v120, v120
	v_exp_f32_e32 v121, v121
	v_exp_f32_e32 v122, v122
	v_exp_f32_e32 v123, v123
	v_exp_f32_e32 v124, v124
	v_exp_f32_e32 v125, v125
	v_exp_f32_e32 v126, v126
	v_exp_f32_e32 v127, v127
	v_exp_f32_e32 v192, v192
	v_add_f32_e32 v64, v64, v112
	v_exp_f32_e32 v193, v193
	v_add_f32_e32 v65, v65, v113
	v_exp_f32_e32 v194, v194
	v_add_f32_e32 v66, v66, v114
	v_exp_f32_e32 v195, v195
	v_add_f32_e32 v67, v67, v115
	v_exp_f32_e32 v196, v196
	v_add_f32_e32 v64, v64, v116
	v_exp_f32_e32 v197, v197
	v_add_f32_e32 v65, v65, v117
	v_exp_f32_e32 v198, v198
	v_add_f32_e32 v66, v66, v118
	v_exp_f32_e32 v199, v199
	v_add_f32_e32 v67, v67, v119
	v_exp_f32_e32 v200, v200
	v_add_f32_e32 v64, v64, v120
	v_exp_f32_e32 v201, v201
	v_add_f32_e32 v65, v65, v121
	v_exp_f32_e32 v202, v202
	v_add_f32_e32 v66, v66, v122
	v_exp_f32_e32 v203, v203
	v_add_f32_e32 v67, v67, v123
	v_exp_f32_e32 v204, v204
	v_add_f32_e32 v64, v64, v124
	v_exp_f32_e32 v205, v205
	v_add_f32_e32 v65, v65, v125
	v_exp_f32_e32 v206, v206
	v_add_f32_e32 v66, v66, v126
	v_exp_f32_e32 v207, v207
	v_add_f32_e32 v67, v67, v127
	v_cvt_pk_bf16_f32 v208, v112, v113
	v_cvt_pk_bf16_f32 v209, v114, v115
	v_cvt_pk_bf16_f32 v210, v116, v117
	v_cvt_pk_bf16_f32 v211, v118, v119
	v_cvt_pk_bf16_f32 v212, v120, v121
	v_cvt_pk_bf16_f32 v213, v122, v123
	v_cvt_pk_bf16_f32 v214, v124, v125
	v_cvt_pk_bf16_f32 v215, v126, v127
	v_add_f32_e32 v64, v64, v192
	v_add_f32_e32 v65, v65, v193
	v_add_f32_e32 v66, v66, v194
	v_add_f32_e32 v67, v67, v195
	v_add_f32_e32 v64, v64, v196
	v_add_f32_e32 v65, v65, v197
	v_add_f32_e32 v66, v66, v198
	v_add_f32_e32 v67, v67, v199
	v_permlane32_swap_b32_e32 v208, v210
	v_permlane32_swap_b32_e32 v209, v211
	v_permlane32_swap_b32_e32 v212, v214
	v_permlane32_swap_b32_e32 v213, v215
	v_add_f32_e32 v64, v64, v200
	v_add_f32_e32 v65, v65, v201
	v_add_f32_e32 v66, v66, v202
	v_add_f32_e32 v67, v67, v203
	v_add_f32_e32 v64, v64, v204
	v_add_f32_e32 v65, v65, v205
	v_add_f32_e32 v66, v66, v206
	v_add_f32_e32 v67, v67, v207
	v_cvt_pk_bf16_f32 v216, v192, v193
	v_cvt_pk_bf16_f32 v217, v194, v195
	v_cvt_pk_bf16_f32 v218, v196, v197
	v_cvt_pk_bf16_f32 v219, v198, v199
	v_cvt_pk_bf16_f32 v220, v200, v201
	v_cvt_pk_bf16_f32 v221, v202, v203
	v_cvt_pk_bf16_f32 v222, v204, v205
	v_cvt_pk_bf16_f32 v223, v206, v207
	s_nop 1
	v_permlane32_swap_b32_e32 v216, v218
	v_permlane32_swap_b32_e32 v217, v219
	v_permlane32_swap_b32_e32 v220, v222
	v_permlane32_swap_b32_e32 v221, v223
	s_waitcnt vmcnt(0)
	s_barrier
	s_setprio 0
	ds_read_b64_tr_b16 v[84:85], v168 offset:0
	ds_read_b64_tr_b16 v[86:87], v168 offset:2048
	ds_read_b64_tr_b16 v[88:89], v168 offset:4096
	ds_read_b64_tr_b16 v[90:91], v168 offset:6144
	ds_read_b64_tr_b16 v[92:93], v168 offset:8192
	ds_read_b64_tr_b16 v[94:95], v168 offset:10240
	ds_read_b64_tr_b16 v[128:129], v168 offset:12288
	ds_read_b64_tr_b16 v[130:131], v168 offset:14336
	ds_read_b64_tr_b16 v[132:133], v168 offset:512
	ds_read_b64_tr_b16 v[134:135], v168 offset:2560
	ds_read_b64_tr_b16 v[140:141], v168 offset:4608
	ds_read_b64_tr_b16 v[142:143], v168 offset:6656
	ds_read_b64_tr_b16 v[152:153], v168 offset:8704
	ds_read_b64_tr_b16 v[154:155], v168 offset:10752
	s_waitcnt lgkmcnt(12)
	v_mfma_f32_32x32x16_bf16 v[0:15], v[208:211], v[84:87], v[0:15]
	ds_read_b64_tr_b16 v[160:161], v168 offset:12800
	ds_read_b64_tr_b16 v[162:163], v168 offset:14848
	s_waitcnt lgkmcnt(12)
	v_mfma_f32_32x32x16_bf16 v[0:15], v[212:215], v[88:91], v[0:15]
	ds_read_b64_tr_b16 v[84:85], v168 offset:1024
	ds_read_b64_tr_b16 v[86:87], v168 offset:3072
	s_waitcnt lgkmcnt(12)
	v_mfma_f32_32x32x16_bf16 v[0:15], v[216:219], v[92:95], v[0:15]
	ds_read_b64_tr_b16 v[88:89], v168 offset:5120
	ds_read_b64_tr_b16 v[90:91], v168 offset:7168
	s_waitcnt lgkmcnt(12)
	v_mfma_f32_32x32x16_bf16 v[0:15], v[220:223], v[128:131], v[0:15]
	ds_read_b64_tr_b16 v[92:93], v168 offset:9216
	ds_read_b64_tr_b16 v[94:95], v168 offset:11264
	s_waitcnt lgkmcnt(12)
	v_mfma_f32_32x32x16_bf16 v[16:31], v[208:211], v[132:135], v[16:31]
	ds_read_b64_tr_b16 v[128:129], v168 offset:13312
	ds_read_b64_tr_b16 v[130:131], v168 offset:15360
	s_waitcnt lgkmcnt(12)
	v_mfma_f32_32x32x16_bf16 v[16:31], v[212:215], v[140:143], v[16:31]
	ds_read_b64_tr_b16 v[132:133], v168 offset:1536
	ds_read_b64_tr_b16 v[134:135], v168 offset:3584
	s_waitcnt lgkmcnt(12)
	v_mfma_f32_32x32x16_bf16 v[16:31], v[216:219], v[152:155], v[16:31]
	ds_read_b64_tr_b16 v[140:141], v168 offset:5632
	ds_read_b64_tr_b16 v[142:143], v168 offset:7680
	s_waitcnt lgkmcnt(12)
	v_mfma_f32_32x32x16_bf16 v[16:31], v[220:223], v[160:163], v[16:31]
	ds_read_b64_tr_b16 v[152:153], v168 offset:9728
	ds_read_b64_tr_b16 v[154:155], v168 offset:11776
	s_waitcnt lgkmcnt(12)
	v_mfma_f32_32x32x16_bf16 v[32:47], v[208:211], v[84:87], v[32:47]
	ds_read_b64_tr_b16 v[160:161], v168 offset:13824
	ds_read_b64_tr_b16 v[162:163], v168 offset:15872
	v_xor_b32_e32 v168, 0x4000, v168
	s_waitcnt lgkmcnt(12)
	v_mfma_f32_32x32x16_bf16 v[32:47], v[212:215], v[88:91], v[32:47]
	s_waitcnt lgkmcnt(10)
	v_mfma_f32_32x32x16_bf16 v[32:47], v[216:219], v[92:95], v[32:47]
	s_waitcnt lgkmcnt(8)
	v_mfma_f32_32x32x16_bf16 v[32:47], v[220:223], v[128:131], v[32:47]
	s_waitcnt lgkmcnt(6)
	v_mfma_f32_32x32x16_bf16 v[48:63], v[208:211], v[132:135], v[48:63]
	s_waitcnt lgkmcnt(4)
	v_mfma_f32_32x32x16_bf16 v[48:63], v[212:215], v[140:143], v[48:63]
	s_waitcnt lgkmcnt(2)
	v_mfma_f32_32x32x16_bf16 v[48:63], v[216:219], v[152:155], v[48:63]
	s_waitcnt lgkmcnt(0)
	v_mfma_f32_32x32x16_bf16 v[48:63], v[220:223], v[160:163], v[48:63]
	s_barrier
	s_barrier
	s_branch .Lat_done
; #define SBAR() __builtin_amdgcn_sched_barrier(0)
; #define KFRAG(d0, row) (*reinterpret_cast<const bf16x8*>(Ks + KSWZ((row), (half * 64 + (d0) * 16 + hi * 8) * 2)))
; __device__ __forceinline__ void qkt(f32x16& p0, f32x16& p1, const char* Ks, const bf16x8* qr, float c0, int r32, int hi, int half) {
;     ...
;     bf16x8 a0 = KFRAG(0, r32), a1 = KFRAG(0, 32 + r32), b0 = KFRAG(1, r32), b1 = KFRAG(1, 32 + r32);
;     SBAR();
; #pragma unroll
;     for (int r = 0; r < 16; ++r) { p0[r] = c0; p1[r] = c0; }
;     SBAR();
;     p0 = __builtin_amdgcn_mfma_f32_32x32x16_bf16(a0, qr[0], p0, 0, 0, 0); p1 = __builtin_amdgcn_mfma_f32_32x32x16_bf16(a1, qr[0], p1, 0, 0, 0);
;     a0 = KFRAG(2, r32); a1 = KFRAG(2, 32 + r32);
;     SBAR();
;     p0 = __builtin_amdgcn_mfma_f32_32x32x16_bf16(b0, qr[1], p0, 0, 0, 0); p1 = __builtin_amdgcn_mfma_f32_32x32x16_bf16(b1, qr[1], p1, 0, 0, 0);
;     b0 = KFRAG(3, r32); b1 = KFRAG(3, 32 + r32);
;     SBAR();
;     p0 = __builtin_amdgcn_mfma_f32_32x32x16_bf16(a0, qr[2], p0, 0, 0, 0); p1 = __builtin_amdgcn_mfma_f32_32x32x16_bf16(a1, qr[2], p1, 0, 0, 0);
;     p0 = __builtin_amdgcn_mfma_f32_32x32x16_bf16(b0, qr[3], p0, 0, 0, 0); p1 = __builtin_amdgcn_mfma_f32_32x32x16_bf16(b1, qr[3], p1, 0, 0, 0);
.Lat_g1:
	s_barrier
	s_setprio 0
	ds_read_b128 v[224:227], v164
	ds_read_b128 v[228:231], v164 offset:8192
	ds_read_b128 v[232:235], v165
	ds_read_b128 v[236:239], v165 offset:8192
	ds_read_b128 v[240:243], v166
	ds_read_b128 v[244:247], v166 offset:8192
	ds_read_b128 v[248:251], v167
	ds_read_b128 v[188:191], v167 offset:8192
	v_xor_b32_e32 v164, 0x4000, v164
	v_xor_b32_e32 v165, 0x4000, v165
	v_xor_b32_e32 v166, 0x4000, v166
	v_xor_b32_e32 v167, 0x4000, v167
	s_waitcnt lgkmcnt(7)
	v_mfma_f32_32x32x16_bf16 v[112:127], v[224:227], v[108:111], v[68:83]
	s_waitcnt lgkmcnt(6)
	v_mfma_f32_32x32x16_bf16 v[192:207], v[228:231], v[108:111], v[68:83]
	s_waitcnt lgkmcnt(5)
	v_mfma_f32_32x32x16_bf16 v[112:127], v[232:235], v[104:107], v[112:127]
	s_waitcnt lgkmcnt(4)
	v_mfma_f32_32x32x16_bf16 v[192:207], v[236:239], v[104:107], v[192:207]
	s_waitcnt lgkmcnt(3)
	v_mfma_f32_32x32x16_bf16 v[112:127], v[240:243], v[100:103], v[112:127]
	s_waitcnt lgkmcnt(2)
	v_mfma_f32_32x32x16_bf16 v[192:207], v[244:247], v[100:103], v[192:207]
	s_waitcnt lgkmcnt(1)
	v_mfma_f32_32x32x16_bf16 v[112:127], v[248:251], v[96:99], v[112:127]
	s_waitcnt lgkmcnt(0)
	v_mfma_f32_32x32x16_bf16 v[192:207], v[188:191], v[96:99], v[192:207]
	s_nop 7
	s_nop 3
	s_barrier

; #define SBAR() __builtin_amdgcn_sched_barrier(0)
; #define KFRAG(d0, row) (*reinterpret_cast<const bf16x8*>(Ks + KSWZ((row), (half * 64 + (d0) * 16 + hi * 8) * 2)))
; __device__ __forceinline__ void expHalf(f32x16& p0) {
; #pragma unroll
;     for (int r = 0; r < 16; ++r) p0[r] = __builtin_amdgcn_exp2f(p0[r]);
; }
; __device__ __forceinline__ void finishSM(f32x16& p0, f32x16& p1, float& l_reg, bf16x8& pa0, bf16x8& pa1, bf16x8& pa2, bf16x8& pa3) {
;     float ps = 0;
; #pragma unroll
;     for (int r = 0; r < 16; ++r) ps += p0[r];
; #pragma unroll
;     for (int r = 0; r < 16; ++r) ps += p1[r];
;     l_reg += ps;
;     ...
;     PK4(p0, 0, pa0); PK4(p0, 8, pa1); PK4(p1, 0, pa2); PK4(p1, 8, pa3);
;     ...
; }
; __device__ __forceinline__ void qkt(f32x16& p0, f32x16& p1, const char* Ks, const bf16x8* qr, float c0, int r32, int hi, int half) {
;     ...
;     bf16x8 a0 = KFRAG(0, r32), a1 = KFRAG(0, 32 + r32), b0 = KFRAG(1, r32), b1 = KFRAG(1, 32 + r32);
;     SBAR();
; #pragma unroll
;     for (int r = 0; r < 16; ++r) { p0[r] = c0; p1[r] = c0; }
;     SBAR();
;     p0 = __builtin_amdgcn_mfma_f32_32x32x16_bf16(a0, qr[0], p0, 0, 0, 0); p1 = __builtin_amdgcn_mfma_f32_32x32x16_bf16(a1, qr[0], p1, 0, 0, 0);
;     a0 = KFRAG(2, r32); a1 = KFRAG(2, 32 + r32);
;     SBAR();
;     p0 = __builtin_amdgcn_mfma_f32_32x32x16_bf16(b0, qr[1], p0, 0, 0, 0); p1 = __builtin_amdgcn_mfma_f32_32x32x16_bf16(b1, qr[1], p1, 0, 0, 0);
;     b0 = KFRAG(3, r32); b1 = KFRAG(3, 32 + r32);
;     SBAR();
;     p0 = __builtin_amdgcn_mfma_f32_32x32x16_bf16(a0, qr[2], p0, 0, 0, 0); p1 = __builtin_amdgcn_mfma_f32_32x32x16_bf16(a1, qr[2], p1, 0, 0, 0);
;     p0 = __builtin_amdgcn_mfma_f32_32x32x16_bf16(b0, qr[3], p0, 0, 0, 0); p1 = __builtin_amdgcn_mfma_f32_32x32x16_bf16(b1, qr[3], p1, 0, 0, 0);
.Lat_far_g1l:
	s_mov_b32 m0, s31
	s_add_u32 s7, s31, 0x2000
	global_load_lds_dwordx4 v169, s[24:25]
	v_exp_f32_e32 v112, v112
	v_exp_f32_e32 v113, v113
	v_exp_f32_e32 v114, v114
	v_exp_f32_e32 v115, v115
	v_exp_f32_e32 v116, v116
	v_exp_f32_e32 v117, v117
	v_exp_f32_e32 v118, v118
	v_exp_f32_e32 v119, v119
	s_mov_b32 m0, s7
	s_xor_b32 s31, s31, 0x4000
	global_load_lds_dwordx4 v170, s[24:25]
	s_add_u32 s24, s24, 0x50000
	s_addc_u32 s25, s25, 0
	v_exp_f32_e32 v120, v120
	v_exp_f32_e32 v121, v121
	v_exp_f32_e32 v122, v122
	v_exp_f32_e32 v123, v123
	v_exp_f32_e32 v124, v124
	v_exp_f32_e32 v125, v125
	v_exp_f32_e32 v126, v126
	v_exp_f32_e32 v127, v127
	s_mov_b32 m0, s33
	s_add_u32 s7, s33, 0x2000
	global_load_lds_dwordx4 v171, s[26:27]
	v_exp_f32_e32 v192, v192
	v_add_f32_e32 v64, v64, v112
	v_exp_f32_e32 v193, v193
	v_add_f32_e32 v65, v65, v113
	v_exp_f32_e32 v194, v194
	v_add_f32_e32 v66, v66, v114
	v_exp_f32_e32 v195, v195
	v_add_f32_e32 v67, v67, v115
	v_exp_f32_e32 v196, v196
	v_add_f32_e32 v64, v64, v116
	v_exp_f32_e32 v197, v197
	v_add_f32_e32 v65, v65, v117
	s_mov_b32 m0, s7
	s_xor_b32 s33, s33, 0x4000
	global_load_lds_dwordx4 v172, s[26:27]
	s_add_u32 s26, s26, 0x50000
	s_addc_u32 s27, s27, 0
	v_exp_f32_e32 v198, v198
	v_add_f32_e32 v66, v66, v118
	v_exp_f32_e32 v199, v199
	v_add_f32_e32 v67, v67, v119
	v_exp_f32_e32 v200, v200
	v_add_f32_e32 v64, v64, v120
	v_exp_f32_e32 v201, v201
	v_add_f32_e32 v65, v65, v121
	v_exp_f32_e32 v202, v202
	v_add_f32_e32 v66, v66, v122
	v_exp_f32_e32 v203, v203
	v_add_f32_e32 v67, v67, v123
	v_exp_f32_e32 v204, v204
	v_add_f32_e32 v64, v64, v124
	v_exp_f32_e32 v205, v205
	v_add_f32_e32 v65, v65, v125
	v_exp_f32_e32 v206, v206
	v_add_f32_e32 v66, v66, v126
	v_exp_f32_e32 v207, v207
	v_add_f32_e32 v67, v67, v127
	v_cvt_pk_bf16_f32 v208, v112, v113
	v_cvt_pk_bf16_f32 v209, v114, v115
	v_cvt_pk_bf16_f32 v210, v116, v117
	v_cvt_pk_bf16_f32 v211, v118, v119
	v_cvt_pk_bf16_f32 v212, v120, v121
	v_cvt_pk_bf16_f32 v213, v122, v123
	v_cvt_pk_bf16_f32 v214, v124, v125
	v_cvt_pk_bf16_f32 v215, v126, v127
	v_add_f32_e32 v64, v64, v192
	v_add_f32_e32 v65, v65, v193
	v_add_f32_e32 v66, v66, v194
	v_add_f32_e32 v67, v67, v195
	v_add_f32_e32 v64, v64, v196
	v_add_f32_e32 v65, v65, v197
	v_add_f32_e32 v66, v66, v198
	v_add_f32_e32 v67, v67, v199
	v_permlane32_swap_b32_e32 v208, v210
	v_permlane32_swap_b32_e32 v209, v211
	v_permlane32_swap_b32_e32 v212, v214
	v_permlane32_swap_b32_e32 v213, v215
	v_add_f32_e32 v64, v64, v200
	v_add_f32_e32 v65, v65, v201
	v_add_f32_e32 v66, v66, v202
	v_add_f32_e32 v67, v67, v203
	v_add_f32_e32 v64, v64, v204
	v_add_f32_e32 v65, v65, v205
	v_add_f32_e32 v66, v66, v206
	v_add_f32_e32 v67, v67, v207
	v_cvt_pk_bf16_f32 v216, v192, v193
	v_cvt_pk_bf16_f32 v217, v194, v195
	v_cvt_pk_bf16_f32 v218, v196, v197
	v_cvt_pk_bf16_f32 v219, v198, v199
	v_cvt_pk_bf16_f32 v220, v200, v201
	v_cvt_pk_bf16_f32 v221, v202, v203
	v_cvt_pk_bf16_f32 v222, v204, v205
	v_cvt_pk_bf16_f32 v223, v206, v207
	s_add_i32 s101, s23, 64
	s_cmp_ge_i32 s101, s30
	s_cselect_b32 s6, s100, s99
	s_cmp_le_i32 s101, s29
	s_cselect_b32 s6, s98, s6
	s_nop 0
	v_permlane32_swap_b32_e32 v216, v218
	v_permlane32_swap_b32_e32 v217, v219
	v_permlane32_swap_b32_e32 v220, v222
	v_permlane32_swap_b32_e32 v221, v223
	s_cmp_lg_u32 s6, s9
	s_cbranch_scc0 .Lat_c0same_g1l
	s_mov_b32 s9, s6
	v_mov_b32_e32 v68, s9
	v_mov_b32_e32 v69, s9
	v_mov_b32_e32 v70, s9
	v_mov_b32_e32 v71, s9
	v_mov_b32_e32 v72, s9
	v_mov_b32_e32 v73, s9
	v_mov_b32_e32 v74, s9
	v_mov_b32_e32 v75, s9
	v_mov_b32_e32 v76, s9
	v_mov_b32_e32 v77, s9
	v_mov_b32_e32 v78, s9
	v_mov_b32_e32 v79, s9
	v_mov_b32_e32 v80, s9
	v_mov_b32_e32 v81, s9
	v_mov_b32_e32 v82, s9
	v_mov_b32_e32 v83, s9
.Lat_c0same_g1l:
	ds_read_b128 v[224:227], v164
	ds_read_b128 v[228:231], v164 offset:8192
	ds_read_b128 v[232:235], v165
	ds_read_b128 v[236:239], v165 offset:8192
	ds_read_b128 v[240:243], v166
	ds_read_b128 v[244:247], v166 offset:8192
	ds_read_b128 v[248:251], v167
	ds_read_b128 v[188:191], v167 offset:8192
	v_xor_b32_e32 v164, 0x4000, v164
	v_xor_b32_e32 v165, 0x4000, v165
	v_xor_b32_e32 v166, 0x4000, v166
	v_xor_b32_e32 v167, 0x4000, v167
	s_barrier
	s_setprio 0
	s_waitcnt lgkmcnt(7)
	v_mfma_f32_32x32x16_bf16 v[112:127], v[224:227], v[108:111], v[68:83]
	s_waitcnt lgkmcnt(6)
	v_mfma_f32_32x32x16_bf16 v[192:207], v[228:231], v[108:111], v[68:83]
	ds_read_b64_tr_b16 v[84:85], v168 offset:0
	ds_read_b64_tr_b16 v[86:87], v168 offset:2048
	s_waitcnt lgkmcnt(7)
	v_mfma_f32_32x32x16_bf16 v[112:127], v[232:235], v[104:107], v[112:127]
	ds_read_b64_tr_b16 v[88:89], v168 offset:4096
	ds_read_b64_tr_b16 v[90:91], v168 offset:6144
	s_waitcnt lgkmcnt(8)
	v_mfma_f32_32x32x16_bf16 v[192:207], v[236:239], v[104:107], v[192:207]
	ds_read_b64_tr_b16 v[92:93], v168 offset:8192
	ds_read_b64_tr_b16 v[94:95], v168 offset:10240
	s_waitcnt lgkmcnt(9)
	v_mfma_f32_32x32x16_bf16 v[112:127], v[240:243], v[100:103], v[112:127]
	ds_read_b64_tr_b16 v[128:129], v168 offset:12288
	ds_read_b64_tr_b16 v[130:131], v168 offset:14336
	s_waitcnt lgkmcnt(10)
	v_mfma_f32_32x32x16_bf16 v[192:207], v[244:247], v[100:103], v[192:207]
	ds_read_b64_tr_b16 v[132:133], v168 offset:512
	ds_read_b64_tr_b16 v[134:135], v168 offset:2560
	s_waitcnt lgkmcnt(11)
	v_mfma_f32_32x32x16_bf16 v[112:127], v[248:251], v[96:99], v[112:127]
	ds_read_b64_tr_b16 v[140:141], v168 offset:4608
	ds_read_b64_tr_b16 v[142:143], v168 offset:6656
	s_waitcnt lgkmcnt(12)
	v_mfma_f32_32x32x16_bf16 v[192:207], v[188:191], v[96:99], v[192:207]
	ds_read_b64_tr_b16 v[152:153], v168 offset:8704
	ds_read_b64_tr_b16 v[154:155], v168 offset:10752
	s_waitcnt lgkmcnt(12)
; #define SBAR() __builtin_amdgcn_sched_barrier(0)
; #define PVLOAD(D0, X) do { X[0] = tr_read<v_rd_off(D0, 0, 0)>(vb); X[1] = tr_read<v_rd_off(D0, 0, 1)>(vb); X[2] = tr_read<v_rd_off(D0, 1, 0)>(vb); X[3] = tr_read<v_rd_off(D0, 1, 1)>(vb); \
;     X[4] = tr_read<v_rd_off(D0, 2, 0)>(vb); X[5] = tr_read<v_rd_off(D0, 2, 1)>(vb); X[6] = tr_read<v_rd_off(D0, 3, 0)>(vb); X[7] = tr_read<v_rd_off(D0, 3, 1)>(vb); } while (0)
; #define PVMMA(OD, X) do { OD = __builtin_amdgcn_mfma_f32_32x32x16_bf16(pa0, PVPK(X[0], X[1]), OD, 0, 0, 0); OD = __builtin_amdgcn_mfma_f32_32x32x16_bf16(pa1, PVPK(X[2], X[3]), OD, 0, 0, 0); \
;     OD = __builtin_amdgcn_mfma_f32_32x32x16_bf16(pa2, PVPK(X[4], X[5]), OD, 0, 0, 0); OD = __builtin_amdgcn_mfma_f32_32x32x16_bf16(pa3, PVPK(X[6], X[7]), OD, 0, 0, 0); } while (0)
; #define PVWAIT() do { asm volatile("s_waitcnt lgkmcnt(0)" ::: "memory"); SBAR(); } while (0)
; #define PVEXP(P, B, N) do { _Pragma("unroll") for (int r = (B); r < (B) + (N); ++r) P[r] = __builtin_amdgcn_exp2f(P[r]); } while (0)
; template <int NB> __device__ __forceinline__ void pv_blocks(f32x16* o, int vb, bf16x8 pa0, bf16x8 pa1, bf16x8 pa2, bf16x8 pa3, f32x16& pe0, f32x16& pe1) {
;     s16x4 x[8], y[8];
;     ...
;     PVLOAD(0, x); PVWAIT();
;     if (NB == 4) {
;         PVLOAD(1, y); SBAR(); PVMMA(o[0], x); PVEXP(pe0, 0, 8); SBAR(); PVWAIT();
;         PVLOAD(2, x); SBAR(); PVMMA(o[1], y); PVEXP(pe0, 8, 8); SBAR(); PVWAIT();
;         PVLOAD(3, y); SBAR(); PVMMA(o[2], x); PVEXP(pe1, 0, 8); SBAR(); PVWAIT();
;         PVMMA(o[3], y); PVEXP(pe1, 8, 8);
;     } else {
;         PVLOAD(1, y); SBAR(); PVMMA(o[0], x); PVEXP(pe0, 0, 16); SBAR(); PVWAIT();
;         PVMMA(o[1], y); PVEXP(pe1, 0, 16);
;     }
;     ...
; }
; template <int MODE>
; __device__ __forceinline__ void attn_unit(const UnitArgs& A, char* lds, const int wave_) {
;     ...
;             if (zone_of(t) == 1) { const int k0 = 64 * t, qw0 = A.q0 + 32 * qb;
;                 const float* b = lutA + A.h * LUTA_STRIDE + (k0 - qw0 - r32 + 4 * hi + 320);
; #pragma unroll
;                 for (int r = 0; r < 16; ++r) { const int c = (r & 3) + 8 * (r >> 2); p0[r] += b[c]; p1[r] += b[32 + c]; } }
	v_mfma_f32_32x32x16_bf16 v[0:15], v[208:211], v[84:87], v[0:15]
	ds_read_b64_tr_b16 v[160:161], v168 offset:12800
	ds_read_b64_tr_b16 v[162:163], v168 offset:14848
	s_waitcnt lgkmcnt(12)
	v_mfma_f32_32x32x16_bf16 v[0:15], v[212:215], v[88:91], v[0:15]
	ds_read_b64_tr_b16 v[84:85], v168 offset:1024
	ds_read_b64_tr_b16 v[86:87], v168 offset:3072
	s_waitcnt lgkmcnt(12)
	v_mfma_f32_32x32x16_bf16 v[0:15], v[216:219], v[92:95], v[0:15]
	ds_read_b64_tr_b16 v[88:89], v168 offset:5120
	ds_read_b64_tr_b16 v[90:91], v168 offset:7168
	s_waitcnt lgkmcnt(12)
	v_mfma_f32_32x32x16_bf16 v[0:15], v[220:223], v[128:131], v[0:15]
	ds_read_b64_tr_b16 v[92:93], v168 offset:9216
	ds_read_b64_tr_b16 v[94:95], v168 offset:11264
	s_waitcnt lgkmcnt(12)
	v_mfma_f32_32x32x16_bf16 v[16:31], v[208:211], v[132:135], v[16:31]
	ds_read_b64_tr_b16 v[128:129], v168 offset:13312
	ds_read_b64_tr_b16 v[130:131], v168 offset:15360
	s_waitcnt lgkmcnt(12)
	v_mfma_f32_32x32x16_bf16 v[16:31], v[212:215], v[140:143], v[16:31]
	ds_read_b64_tr_b16 v[132:133], v168 offset:1536
	ds_read_b64_tr_b16 v[134:135], v168 offset:3584
	s_waitcnt lgkmcnt(12)
	v_mfma_f32_32x32x16_bf16 v[16:31], v[216:219], v[152:155], v[16:31]
	ds_read_b64_tr_b16 v[140:141], v168 offset:5632
	ds_read_b64_tr_b16 v[142:143], v168 offset:7680
	s_waitcnt lgkmcnt(12)
	v_mfma_f32_32x32x16_bf16 v[16:31], v[220:223], v[160:163], v[16:31]
	ds_read_b64_tr_b16 v[152:153], v168 offset:9728
	ds_read_b64_tr_b16 v[154:155], v168 offset:11776
	s_waitcnt lgkmcnt(12)
	v_mfma_f32_32x32x16_bf16 v[32:47], v[208:211], v[84:87], v[32:47]
	ds_read_b64_tr_b16 v[160:161], v168 offset:13824
	ds_read_b64_tr_b16 v[162:163], v168 offset:15872
	v_xor_b32_e32 v168, 0x4000, v168
	s_waitcnt lgkmcnt(12)
	v_mfma_f32_32x32x16_bf16 v[32:47], v[212:215], v[88:91], v[32:47]
	s_waitcnt lgkmcnt(10)
	v_mfma_f32_32x32x16_bf16 v[32:47], v[216:219], v[92:95], v[32:47]
	s_waitcnt lgkmcnt(8)
	v_mfma_f32_32x32x16_bf16 v[32:47], v[220:223], v[128:131], v[32:47]
	s_waitcnt lgkmcnt(6)
	v_mfma_f32_32x32x16_bf16 v[48:63], v[208:211], v[132:135], v[48:63]
	s_waitcnt lgkmcnt(4)
	v_mfma_f32_32x32x16_bf16 v[48:63], v[212:215], v[140:143], v[48:63]
	s_waitcnt lgkmcnt(2)
	v_mfma_f32_32x32x16_bf16 v[48:63], v[216:219], v[152:155], v[48:63]
	s_waitcnt lgkmcnt(0)
	v_mfma_f32_32x32x16_bf16 v[48:63], v[220:223], v[160:163], v[48:63]
	s_add_i32 s34, s34, 1
	s_add_i32 s23, s23, 64
	s_addk_i32 s35, 0x100
	s_waitcnt vmcnt(0)
	s_barrier
	s_cmp_lt_u32 s34, s20
	s_cbranch_scc1 .Lat_g1_loop
	s_setprio 1
	s_cmp_gt_i32 s23, s29
	s_cselect_b32 s101, 1, 0
	s_cmp_lt_i32 s23, s30
	s_cselect_b32 s6, 1, 0
	s_and_b32 s101, s101, s6
	s_cbranch_scc0 .Lat_far_g1p
	v_add_u32_e32 v181, s35, v174
	ds_read2_b32 v[224:225], v181 offset0:0 offset1:1
	ds_read2_b32 v[226:227], v181 offset0:2 offset1:3
	ds_read2_b32 v[228:229], v181 offset0:8 offset1:9
	ds_read2_b32 v[230:231], v181 offset0:10 offset1:11
	ds_read2_b32 v[232:233], v181 offset0:16 offset1:17
	ds_read2_b32 v[234:235], v181 offset0:18 offset1:19
	ds_read2_b32 v[236:237], v181 offset0:24 offset1:25
	ds_read2_b32 v[238:239], v181 offset0:26 offset1:27
	s_waitcnt lgkmcnt(4)
	ds_read2_b32 v[240:241], v181 offset0:32 offset1:33
	ds_read2_b32 v[242:243], v181 offset0:34 offset1:35
	ds_read2_b32 v[244:245], v181 offset0:40 offset1:41
	ds_read2_b32 v[246:247], v181 offset0:42 offset1:43
	ds_read2_b32 v[248:249], v181 offset0:48 offset1:49
	ds_read2_b32 v[250:251], v181 offset0:50 offset1:51
	ds_read2_b32 v[188:189], v181 offset0:56 offset1:57
	ds_read2_b32 v[190:191], v181 offset0:58 offset1:59
	s_waitcnt lgkmcnt(8)
	v_add_f32_e32 v112, v112, v224
	v_add_f32_e32 v113, v113, v225
	v_add_f32_e32 v114, v114, v226
	v_add_f32_e32 v115, v115, v227
	v_add_f32_e32 v116, v116, v228
	v_add_f32_e32 v117, v117, v229
	v_add_f32_e32 v118, v118, v230
	v_add_f32_e32 v119, v119, v231
	v_add_f32_e32 v120, v120, v232
	v_add_f32_e32 v121, v121, v233
	v_add_f32_e32 v122, v122, v234
	v_add_f32_e32 v123, v123, v235
	v_add_f32_e32 v124, v124, v236
	v_add_f32_e32 v125, v125, v237
	v_add_f32_e32 v126, v126, v238
	v_add_f32_e32 v127, v127, v239
	s_waitcnt lgkmcnt(0)
	v_add_f32_e32 v192, v192, v240
	v_add_f32_e32 v193, v193, v241
	v_add_f32_e32 v194, v194, v242
	v_add_f32_e32 v195, v195, v243
	v_add_f32_e32 v196, v196, v244
	v_add_f32_e32 v197, v197, v245
	v_add_f32_e32 v198, v198, v246
	v_add_f32_e32 v199, v199, v247
	v_add_f32_e32 v200, v200, v248
	v_add_f32_e32 v201, v201, v249
	v_add_f32_e32 v202, v202, v250
	v_add_f32_e32 v203, v203, v251
	v_add_f32_e32 v204, v204, v188
	v_add_f32_e32 v205, v205, v189
	v_add_f32_e32 v206, v206, v190
	v_add_f32_e32 v207, v207, v191
; #define SBAR() __builtin_amdgcn_sched_barrier(0)
; #define PVLOAD(D0, X) do { X[0] = tr_read<v_rd_off(D0, 0, 0)>(vb); X[1] = tr_read<v_rd_off(D0, 0, 1)>(vb); X[2] = tr_read<v_rd_off(D0, 1, 0)>(vb); X[3] = tr_read<v_rd_off(D0, 1, 1)>(vb); \
;     X[4] = tr_read<v_rd_off(D0, 2, 0)>(vb); X[5] = tr_read<v_rd_off(D0, 2, 1)>(vb); X[6] = tr_read<v_rd_off(D0, 3, 0)>(vb); X[7] = tr_read<v_rd_off(D0, 3, 1)>(vb); } while (0)
; #define PVMMA(OD, X) do { OD = __builtin_amdgcn_mfma_f32_32x32x16_bf16(pa0, PVPK(X[0], X[1]), OD, 0, 0, 0); OD = __builtin_amdgcn_mfma_f32_32x32x16_bf16(pa1, PVPK(X[2], X[3]), OD, 0, 0, 0); \
;     OD = __builtin_amdgcn_mfma_f32_32x32x16_bf16(pa2, PVPK(X[4], X[5]), OD, 0, 0, 0); OD = __builtin_amdgcn_mfma_f32_32x32x16_bf16(pa3, PVPK(X[6], X[7]), OD, 0, 0, 0); } while (0)
; #define PVWAIT() do { asm volatile("s_waitcnt lgkmcnt(0)" ::: "memory"); SBAR(); } while (0)
; #define PVEXP(P, B, N) do { _Pragma("unroll") for (int r = (B); r < (B) + (N); ++r) P[r] = __builtin_amdgcn_exp2f(P[r]); } while (0)
; __device__ __forceinline__ void expHalf(f32x16& p0) {
; #pragma unroll
;     for (int r = 0; r < 16; ++r) p0[r] = __builtin_amdgcn_exp2f(p0[r]);
; }
; __device__ __forceinline__ void finishSM(f32x16& p0, f32x16& p1, float& l_reg, bf16x8& pa0, bf16x8& pa1, bf16x8& pa2, bf16x8& pa3) {
;     float ps = 0;
; #pragma unroll
;     for (int r = 0; r < 16; ++r) ps += p0[r];
; #pragma unroll
;     for (int r = 0; r < 16; ++r) ps += p1[r];
;     l_reg += ps;
;     ...
;     PK4(p0, 0, pa0); PK4(p0, 8, pa1); PK4(p1, 0, pa2); PK4(p1, 8, pa3);
;     ...
; }
; template <int NB> __device__ __forceinline__ void pv_blocks(f32x16* o, int vb, bf16x8 pa0, bf16x8 pa1, bf16x8 pa2, bf16x8 pa3, f32x16& pe0, f32x16& pe1) {
;     s16x4 x[8], y[8];
;     ...
;     PVLOAD(0, x); PVWAIT();
;     if (NB == 4) {
;         PVLOAD(1, y); SBAR(); PVMMA(o[0], x); PVEXP(pe0, 0, 8); SBAR(); PVWAIT();
;         PVLOAD(2, x); SBAR(); PVMMA(o[1], y); PVEXP(pe0, 8, 8); SBAR(); PVWAIT();
;         PVLOAD(3, y); SBAR(); PVMMA(o[2], x); PVEXP(pe1, 0, 8); SBAR(); PVWAIT();
;         PVMMA(o[3], y); PVEXP(pe1, 8, 8);
;     } else {
;         PVLOAD(1, y); SBAR(); PVMMA(o[0], x); PVEXP(pe0, 0, 16); SBAR(); PVWAIT();
;         PVMMA(o[1], y); PVEXP(pe1, 0, 16);
;     }
;     ...
; }
.Lat_far_g1p:
	v_exp_f32_e32 v112, v112
	v_exp_f32_e32 v113, v113
	v_exp_f32_e32 v114, v114
	v_exp_f32_e32 v115, v115
	v_exp_f32_e32 v116, v116
	v_exp_f32_e32 v117, v117
	v_exp_f32_e32 v118, v118
	v_exp_f32_e32 v119, v119
	v_exp_f32_e32 v120, v120
	v_exp_f32_e32 v121, v121
	v_exp_f32_e32 v122, v122
	v_exp_f32_e32 v123, v123
	v_exp_f32_e32 v124, v124
	v_exp_f32_e32 v125, v125
	v_exp_f32_e32 v126, v126
	v_exp_f32_e32 v127, v127
	v_exp_f32_e32 v192, v192
	v_add_f32_e32 v64, v64, v112
	v_exp_f32_e32 v193, v193
	v_add_f32_e32 v65, v65, v113
	v_exp_f32_e32 v194, v194
	v_add_f32_e32 v66, v66, v114
	v_exp_f32_e32 v195, v195
	v_add_f32_e32 v67, v67, v115
	v_exp_f32_e32 v196, v196
	v_add_f32_e32 v64, v64, v116
	v_exp_f32_e32 v197, v197
	v_add_f32_e32 v65, v65, v117
	v_exp_f32_e32 v198, v198
	v_add_f32_e32 v66, v66, v118
	v_exp_f32_e32 v199, v199
	v_add_f32_e32 v67, v67, v119
	v_exp_f32_e32 v200, v200
	v_add_f32_e32 v64, v64, v120
	v_exp_f32_e32 v201, v201
	v_add_f32_e32 v65, v65, v121
	v_exp_f32_e32 v202, v202
	v_add_f32_e32 v66, v66, v122
	v_exp_f32_e32 v203, v203
	v_add_f32_e32 v67, v67, v123
	v_exp_f32_e32 v204, v204
	v_add_f32_e32 v64, v64, v124
	v_exp_f32_e32 v205, v205
	v_add_f32_e32 v65, v65, v125
	v_exp_f32_e32 v206, v206
	v_add_f32_e32 v66, v66, v126
	v_exp_f32_e32 v207, v207
	v_add_f32_e32 v67, v67, v127
	v_cvt_pk_bf16_f32 v208, v112, v113
	v_cvt_pk_bf16_f32 v209, v114, v115
	v_cvt_pk_bf16_f32 v210, v116, v117
	v_cvt_pk_bf16_f32 v211, v118, v119
	v_cvt_pk_bf16_f32 v212, v120, v121
	v_cvt_pk_bf16_f32 v213, v122, v123
	v_cvt_pk_bf16_f32 v214, v124, v125
	v_cvt_pk_bf16_f32 v215, v126, v127
	v_add_f32_e32 v64, v64, v192
	v_add_f32_e32 v65, v65, v193
	v_add_f32_e32 v66, v66, v194
	v_add_f32_e32 v67, v67, v195
	v_add_f32_e32 v64, v64, v196
	v_add_f32_e32 v65, v65, v197
	v_add_f32_e32 v66, v66, v198
	v_add_f32_e32 v67, v67, v199
	v_permlane32_swap_b32_e32 v208, v210
	v_permlane32_swap_b32_e32 v209, v211
	v_permlane32_swap_b32_e32 v212, v214
	v_permlane32_swap_b32_e32 v213, v215
	v_add_f32_e32 v64, v64, v200
	v_add_f32_e32 v65, v65, v201
	v_add_f32_e32 v66, v66, v202
	v_add_f32_e32 v67, v67, v203
	v_add_f32_e32 v64, v64, v204
	v_add_f32_e32 v65, v65, v205
	v_add_f32_e32 v66, v66, v206
	v_add_f32_e32 v67, v67, v207
	v_cvt_pk_bf16_f32 v216, v192, v193
	v_cvt_pk_bf16_f32 v217, v194, v195
	v_cvt_pk_bf16_f32 v218, v196, v197
	v_cvt_pk_bf16_f32 v219, v198, v199
	v_cvt_pk_bf16_f32 v220, v200, v201
	v_cvt_pk_bf16_f32 v221, v202, v203
	v_cvt_pk_bf16_f32 v222, v204, v205
	v_cvt_pk_bf16_f32 v223, v206, v207
	s_nop 1
	v_permlane32_swap_b32_e32 v216, v218
	v_permlane32_swap_b32_e32 v217, v219
	v_permlane32_swap_b32_e32 v220, v222
	v_permlane32_swap_b32_e32 v221, v223
	s_barrier
	s_setprio 0
	ds_read_b64_tr_b16 v[84:85], v168 offset:0
	ds_read_b64_tr_b16 v[86:87], v168 offset:2048
	ds_read_b64_tr_b16 v[88:89], v168 offset:4096
	ds_read_b64_tr_b16 v[90:91], v168 offset:6144
	ds_read_b64_tr_b16 v[92:93], v168 offset:8192
	ds_read_b64_tr_b16 v[94:95], v168 offset:10240
	ds_read_b64_tr_b16 v[128:129], v168 offset:12288
	ds_read_b64_tr_b16 v[130:131], v168 offset:14336
	ds_read_b64_tr_b16 v[132:133], v168 offset:512
	ds_read_b64_tr_b16 v[134:135], v168 offset:2560
	ds_read_b64_tr_b16 v[140:141], v168 offset:4608
	ds_read_b64_tr_b16 v[142:143], v168 offset:6656
	ds_read_b64_tr_b16 v[152:153], v168 offset:8704
	ds_read_b64_tr_b16 v[154:155], v168 offset:10752
	s_waitcnt lgkmcnt(12)
	v_mfma_f32_32x32x16_bf16 v[0:15], v[208:211], v[84:87], v[0:15]
	ds_read_b64_tr_b16 v[160:161], v168 offset:12800
	ds_read_b64_tr_b16 v[162:163], v168 offset:14848
	s_waitcnt lgkmcnt(12)
	v_mfma_f32_32x32x16_bf16 v[0:15], v[212:215], v[88:91], v[0:15]
	ds_read_b64_tr_b16 v[84:85], v168 offset:1024
	ds_read_b64_tr_b16 v[86:87], v168 offset:3072
	s_waitcnt lgkmcnt(12)
	v_mfma_f32_32x32x16_bf16 v[0:15], v[216:219], v[92:95], v[0:15]
	ds_read_b64_tr_b16 v[88:89], v168 offset:5120
	ds_read_b64_tr_b16 v[90:91], v168 offset:7168
	s_waitcnt lgkmcnt(12)
	v_mfma_f32_32x32x16_bf16 v[0:15], v[220:223], v[128:131], v[0:15]
	ds_read_b64_tr_b16 v[92:93], v168 offset:9216
	ds_read_b64_tr_b16 v[94:95], v168 offset:11264
	s_waitcnt lgkmcnt(12)
	v_mfma_f32_32x32x16_bf16 v[16:31], v[208:211], v[132:135], v[16:31]
	ds_read_b64_tr_b16 v[128:129], v168 offset:13312
	ds_read_b64_tr_b16 v[130:131], v168 offset:15360
	s_waitcnt lgkmcnt(12)
	v_mfma_f32_32x32x16_bf16 v[16:31], v[212:215], v[140:143], v[16:31]
	ds_read_b64_tr_b16 v[132:133], v168 offset:1536
	ds_read_b64_tr_b16 v[134:135], v168 offset:3584
	s_waitcnt lgkmcnt(12)
	v_mfma_f32_32x32x16_bf16 v[16:31], v[216:219], v[152:155], v[16:31]
	ds_read_b64_tr_b16 v[140:141], v168 offset:5632
	ds_read_b64_tr_b16 v[142:143], v168 offset:7680
	s_waitcnt lgkmcnt(12)
	v_mfma_f32_32x32x16_bf16 v[16:31], v[220:223], v[160:163], v[16:31]
	ds_read_b64_tr_b16 v[152:153], v168 offset:9728
	ds_read_b64_tr_b16 v[154:155], v168 offset:11776
	s_waitcnt lgkmcnt(12)
	v_mfma_f32_32x32x16_bf16 v[32:47], v[208:211], v[84:87], v[32:47]
	ds_read_b64_tr_b16 v[160:161], v168 offset:13824
	ds_read_b64_tr_b16 v[162:163], v168 offset:15872
	v_xor_b32_e32 v168, 0x4000, v168
	s_waitcnt lgkmcnt(12)
	v_mfma_f32_32x32x16_bf16 v[32:47], v[212:215], v[88:91], v[32:47]
	s_waitcnt lgkmcnt(10)
	v_mfma_f32_32x32x16_bf16 v[32:47], v[216:219], v[92:95], v[32:47]
	s_waitcnt lgkmcnt(8)
	v_mfma_f32_32x32x16_bf16 v[32:47], v[220:223], v[128:131], v[32:47]
	s_waitcnt lgkmcnt(6)
	v_mfma_f32_32x32x16_bf16 v[48:63], v[208:211], v[132:135], v[48:63]
	s_waitcnt lgkmcnt(4)
	v_mfma_f32_32x32x16_bf16 v[48:63], v[212:215], v[140:143], v[48:63]
	s_waitcnt lgkmcnt(2)
	v_mfma_f32_32x32x16_bf16 v[48:63], v[216:219], v[152:155], v[48:63]
	s_waitcnt lgkmcnt(0)
	v_mfma_f32_32x32x16_bf16 v[48:63], v[220:223], v[160:163], v[48:63]
	s_waitcnt vmcnt(0)
	s_barrier
